# grid-barrier spin loops: s_sleep 3 instead of s_sleep 1 between polls (polling back-off)
# baseline (speedup 1.0000x reference)
.LBB0_74:
	global_load_dword v16, v17, s[40:41] offset:1024 sc1
	s_waitcnt lgkmcnt(0)
	global_load_dword v1, v17, s[40:41] offset:1280 sc1
	global_load_dword v2, v17, s[40:41] offset:1536 sc1
	global_load_dword v3, v17, s[40:41] offset:1792 sc1
	global_load_dword v4, v17, s[40:41] offset:2048 sc1
	global_load_dword v5, v17, s[40:41] offset:2304 sc1
	global_load_dword v6, v17, s[40:41] offset:2560 sc1
	global_load_dword v7, v17, s[40:41] offset:2816 sc1
	global_load_dword v8, v17, s[40:41] offset:3072 sc1
	global_load_dword v9, v17, s[40:41] offset:3328 sc1
	global_load_dword v10, v17, s[40:41] offset:3584 sc1
	global_load_dword v11, v17, s[40:41] offset:3840 sc1
	global_load_dword v12, v17, s[8:9] sc1
	global_load_dword v13, v17, s[10:11] sc1
	global_load_dword v14, v17, s[12:13] sc1
	global_load_dword v15, v17, s[14:15] sc1
	s_mov_b64 s[16:17], -1
	s_mov_b64 s[18:19], -1
	s_waitcnt vmcnt(14)
	v_add_u32_e32 v18, v1, v16
	s_waitcnt vmcnt(13)
	v_add_u32_e32 v18, v18, v2
	s_waitcnt vmcnt(12)
	v_add_u32_e32 v18, v18, v3
	s_waitcnt vmcnt(11)
	v_add_u32_e32 v18, v18, v4
	s_waitcnt vmcnt(10)
	v_add_u32_e32 v18, v18, v5
	s_waitcnt vmcnt(9)
	v_add_u32_e32 v18, v18, v6
	s_waitcnt vmcnt(8)
	v_add_u32_e32 v18, v18, v7
	s_waitcnt vmcnt(7)
	v_add_u32_e32 v18, v18, v8
	s_waitcnt vmcnt(6)
	v_add_u32_e32 v18, v18, v9
	s_waitcnt vmcnt(5)
	v_add_u32_e32 v18, v18, v10
	s_waitcnt vmcnt(4)
	v_add_u32_e32 v18, v18, v11
	s_waitcnt vmcnt(3)
	v_add_u32_e32 v18, v18, v12
	s_waitcnt vmcnt(2)
	v_add_u32_e32 v18, v18, v13
	s_waitcnt vmcnt(1)
	v_add_u32_e32 v18, v18, v14
	s_waitcnt vmcnt(0)
	v_add_u32_e32 v18, v18, v15
	v_cmp_eq_u32_e32 vcc, s21, v18
	s_cbranch_vccnz .LBB0_73
	s_and_b32 s16, s23, 0xff
	s_cmp_eq_u32 s16, 0
	s_mov_b64 s[16:17], -1
	s_mov_b64 s[24:25], -1
	s_sleep 3
	s_cbranch_scc1 .LBB0_78
	s_and_b64 vcc, exec, s[24:25]
	s_cbranch_vccz .LBB0_73

.LBB0_92:
	s_and_b32 s23, s21, 0xff
	s_mov_b64 s[24:25], -1
	s_cmp_lg_u32 s23, 0
	s_mov_b64 s[28:29], -1
	s_sleep 3
	s_cbranch_scc0 .LBB0_95
	s_and_b64 vcc, exec, s[28:29]
	s_cbranch_vccz .LBB0_91

.LBB0_109:
	s_and_b32 s23, s21, 0xff
	s_cmp_lg_u32 s23, 0
	s_mov_b64 s[30:31], -1
	s_sleep 3
	s_cbranch_scc0 .LBB0_112
	s_mov_b64 s[36:37], -1
	s_and_b64 vcc, exec, s[30:31]
	s_cbranch_vccz .LBB0_108

.LBB0_165:
	s_and_b32 s23, s21, 0xff
	s_cmp_lg_u32 s23, 0
	s_mov_b64 s[28:29], -1
	s_sleep 3
	s_cbranch_scc0 .LBB0_168
	s_mov_b64 s[30:31], -1
	s_and_b64 vcc, exec, s[28:29]
	s_cbranch_vccz .LBB0_164

.LBB0_193:
	global_load_dword v17, v18, s[40:41] offset:1024 sc1
	s_waitcnt lgkmcnt(0)
	global_load_dword v2, v18, s[40:41] offset:1280 sc1
	global_load_dword v3, v18, s[40:41] offset:1536 sc1
	global_load_dword v4, v18, s[40:41] offset:1792 sc1
	global_load_dword v5, v18, s[40:41] offset:2048 sc1
	global_load_dword v6, v18, s[40:41] offset:2304 sc1
	global_load_dword v7, v18, s[40:41] offset:2560 sc1
	global_load_dword v8, v18, s[40:41] offset:2816 sc1
	global_load_dword v9, v18, s[40:41] offset:3072 sc1
	global_load_dword v10, v18, s[40:41] offset:3328 sc1
	global_load_dword v11, v18, s[40:41] offset:3584 sc1
	global_load_dword v12, v18, s[40:41] offset:3840 sc1
	global_load_dword v13, v18, s[8:9] sc1
	global_load_dword v14, v18, s[10:11] sc1
	global_load_dword v15, v18, s[12:13] sc1
	global_load_dword v16, v18, s[14:15] sc1
	s_mov_b64 s[16:17], -1
	s_mov_b64 s[18:19], -1
	s_waitcnt vmcnt(14)
	v_add_u32_e32 v19, v2, v17
	s_waitcnt vmcnt(13)
	v_add_u32_e32 v19, v19, v3
	s_waitcnt vmcnt(12)
	v_add_u32_e32 v19, v19, v4
	s_waitcnt vmcnt(11)
	v_add_u32_e32 v19, v19, v5
	s_waitcnt vmcnt(10)
	v_add_u32_e32 v19, v19, v6
	s_waitcnt vmcnt(9)
	v_add_u32_e32 v19, v19, v7
	s_waitcnt vmcnt(8)
	v_add_u32_e32 v19, v19, v8
	s_waitcnt vmcnt(7)
	v_add_u32_e32 v19, v19, v9
	s_waitcnt vmcnt(6)
	v_add_u32_e32 v19, v19, v10
	s_waitcnt vmcnt(5)
	v_add_u32_e32 v19, v19, v11
	s_waitcnt vmcnt(4)
	v_add_u32_e32 v19, v19, v12
	s_waitcnt vmcnt(3)
	v_add_u32_e32 v19, v19, v13
	s_waitcnt vmcnt(2)
	v_add_u32_e32 v19, v19, v14
	s_waitcnt vmcnt(1)
	v_add_u32_e32 v19, v19, v15
	s_waitcnt vmcnt(0)
	v_add_u32_e32 v19, v19, v16
	v_cmp_eq_u32_e32 vcc, s22, v19
	s_cbranch_vccnz .LBB0_192
	s_and_b32 s16, s23, 0xff
	s_cmp_eq_u32 s16, 0
	s_mov_b64 s[16:17], -1
	s_mov_b64 s[20:21], -1
	s_sleep 3
	s_cbranch_scc1 .LBB0_197
	s_and_b64 vcc, exec, s[20:21]
	s_cbranch_vccz .LBB0_192

.LBB0_211:
	s_and_b32 s22, s26, 0xff
	s_mov_b64 s[20:21], -1
	s_cmp_lg_u32 s22, 0
	s_mov_b64 s[24:25], -1
	s_sleep 3
	s_cbranch_scc0 .LBB0_214
	s_and_b64 vcc, exec, s[24:25]
	s_cbranch_vccz .LBB0_210

.LBB0_228:
	s_and_b32 s24, s30, 0xff
	s_cmp_lg_u32 s24, 0
	s_mov_b64 s[26:27], -1
	s_sleep 3
	s_cbranch_scc0 .LBB0_231
	s_mov_b64 s[28:29], -1
	s_and_b64 vcc, exec, s[26:27]
	s_cbranch_vccz .LBB0_227

.LBB0_309:
	s_and_b32 s22, s28, 0xff
	s_cmp_lg_u32 s22, 0
	s_mov_b64 s[24:25], -1
	s_sleep 3
	s_cbranch_scc0 .LBB0_312
	s_mov_b64 s[26:27], -1
	s_and_b64 vcc, exec, s[24:25]
	s_cbranch_vccz .LBB0_308

.LBB0_430:
	s_and_b32 s22, s28, 0xff
	s_mov_b64 s[20:21], -1
	s_cmp_lg_u32 s22, 0
	s_mov_b64 s[26:27], -1
	s_sleep 3
	s_cbranch_scc0 .LBB0_433
	s_and_b64 vcc, exec, s[26:27]
	s_cbranch_vccz .LBB0_429

.LBB0_447:
	s_and_b32 s22, s30, 0xff
	s_cmp_lg_u32 s22, 0
	s_mov_b64 s[26:27], -1
	s_sleep 3
	s_cbranch_scc0 .LBB0_450
	s_mov_b64 s[28:29], -1
	s_and_b64 vcc, exec, s[26:27]
	s_cbranch_vccz .LBB0_446

.LBB0_865:
	global_load_dword v17, v18, s[40:41] offset:1024 sc1
	s_waitcnt lgkmcnt(0)
	global_load_dword v2, v18, s[40:41] offset:1280 sc1
	global_load_dword v3, v18, s[40:41] offset:1536 sc1
	global_load_dword v4, v18, s[40:41] offset:1792 sc1
	global_load_dword v5, v18, s[40:41] offset:2048 sc1
	global_load_dword v6, v18, s[40:41] offset:2304 sc1
	global_load_dword v7, v18, s[40:41] offset:2560 sc1
	global_load_dword v8, v18, s[40:41] offset:2816 sc1
	global_load_dword v9, v18, s[40:41] offset:3072 sc1
	global_load_dword v10, v18, s[40:41] offset:3328 sc1
	global_load_dword v11, v18, s[40:41] offset:3584 sc1
	global_load_dword v12, v18, s[40:41] offset:3840 sc1
	global_load_dword v13, v18, s[8:9] sc1
	global_load_dword v14, v18, s[10:11] sc1
	global_load_dword v15, v18, s[12:13] sc1
	global_load_dword v16, v18, s[14:15] sc1
	s_mov_b64 s[16:17], -1
	s_mov_b64 s[18:19], -1
	s_waitcnt vmcnt(14)
	v_add_u32_e32 v19, v2, v17
	s_waitcnt vmcnt(13)
	v_add_u32_e32 v19, v19, v3
	s_waitcnt vmcnt(12)
	v_add_u32_e32 v19, v19, v4
	s_waitcnt vmcnt(11)
	v_add_u32_e32 v19, v19, v5
	s_waitcnt vmcnt(10)
	v_add_u32_e32 v19, v19, v6
	s_waitcnt vmcnt(9)
	v_add_u32_e32 v19, v19, v7
	s_waitcnt vmcnt(8)
	v_add_u32_e32 v19, v19, v8
	s_waitcnt vmcnt(7)
	v_add_u32_e32 v19, v19, v9
	s_waitcnt vmcnt(6)
	v_add_u32_e32 v19, v19, v10
	s_waitcnt vmcnt(5)
	v_add_u32_e32 v19, v19, v11
	s_waitcnt vmcnt(4)
	v_add_u32_e32 v19, v19, v12
	s_waitcnt vmcnt(3)
	v_add_u32_e32 v19, v19, v13
	s_waitcnt vmcnt(2)
	v_add_u32_e32 v19, v19, v14
	s_waitcnt vmcnt(1)
	v_add_u32_e32 v19, v19, v15
	s_waitcnt vmcnt(0)
	v_add_u32_e32 v19, v19, v16
	v_cmp_eq_u32_e32 vcc, s3, v19
	s_cbranch_vccnz .LBB0_864
	s_and_b32 s16, s22, 0xff
	s_cmp_eq_u32 s16, 0
	s_mov_b64 s[16:17], -1
	s_mov_b64 s[20:21], -1
	s_sleep 3
	s_cbranch_scc1 .LBB0_869
	s_and_b64 vcc, exec, s[20:21]
	s_cbranch_vccz .LBB0_864

.LBB0_883:
	s_and_b32 s22, s3, 0xff
	s_mov_b64 s[20:21], -1
	s_cmp_lg_u32 s22, 0
	s_mov_b64 s[26:27], -1
	s_sleep 3
	s_cbranch_scc0 .LBB0_886
	s_and_b64 vcc, exec, s[26:27]
	s_cbranch_vccz .LBB0_882

.LBB0_900:
	s_and_b32 s26, s3, 0xff
	s_cmp_lg_u32 s26, 0
	s_mov_b64 s[28:29], -1
	s_sleep 3
	s_cbranch_scc0 .LBB0_903
	s_mov_b64 s[30:31], -1
	s_and_b64 vcc, exec, s[28:29]
	s_cbranch_vccz .LBB0_899

.LBB0_1063:
	s_and_b32 s22, s3, 0xff
	s_cmp_lg_u32 s22, 0
	s_mov_b64 s[26:27], -1
	s_sleep 3
	s_cbranch_scc0 .LBB0_1066
	s_mov_b64 s[28:29], -1
	s_and_b64 vcc, exec, s[26:27]
	s_cbranch_vccz .LBB0_1062

.LBB0_1178:
	global_load_dword v17, v18, s[40:41] offset:1024 sc1
	s_waitcnt lgkmcnt(0)
	global_load_dword v2, v18, s[40:41] offset:1280 sc1
	global_load_dword v3, v18, s[40:41] offset:1536 sc1
	global_load_dword v4, v18, s[40:41] offset:1792 sc1
	global_load_dword v5, v18, s[40:41] offset:2048 sc1
	global_load_dword v6, v18, s[40:41] offset:2304 sc1
	global_load_dword v7, v18, s[40:41] offset:2560 sc1
	global_load_dword v8, v18, s[40:41] offset:2816 sc1
	global_load_dword v9, v18, s[40:41] offset:3072 sc1
	global_load_dword v10, v18, s[40:41] offset:3328 sc1
	global_load_dword v11, v18, s[40:41] offset:3584 sc1
	global_load_dword v12, v18, s[40:41] offset:3840 sc1
	global_load_dword v13, v18, s[8:9] sc1
	global_load_dword v14, v18, s[10:11] sc1
	global_load_dword v15, v18, s[16:17] sc1
	global_load_dword v16, v18, s[18:19] sc1
	s_mov_b64 s[20:21], -1
	s_mov_b64 s[22:23], -1
	s_waitcnt vmcnt(14)
	v_add_u32_e32 v19, v2, v17
	s_waitcnt vmcnt(13)
	v_add_u32_e32 v19, v19, v3
	s_waitcnt vmcnt(12)
	v_add_u32_e32 v19, v19, v4
	s_waitcnt vmcnt(11)
	v_add_u32_e32 v19, v19, v5
	s_waitcnt vmcnt(10)
	v_add_u32_e32 v19, v19, v6
	s_waitcnt vmcnt(9)
	v_add_u32_e32 v19, v19, v7
	s_waitcnt vmcnt(8)
	v_add_u32_e32 v19, v19, v8
	s_waitcnt vmcnt(7)
	v_add_u32_e32 v19, v19, v9
	s_waitcnt vmcnt(6)
	v_add_u32_e32 v19, v19, v10
	s_waitcnt vmcnt(5)
	v_add_u32_e32 v19, v19, v11
	s_waitcnt vmcnt(4)
	v_add_u32_e32 v19, v19, v12
	s_waitcnt vmcnt(3)
	v_add_u32_e32 v19, v19, v13
	s_waitcnt vmcnt(2)
	v_add_u32_e32 v19, v19, v14
	s_waitcnt vmcnt(1)
	v_add_u32_e32 v19, v19, v15
	s_waitcnt vmcnt(0)
	v_add_u32_e32 v19, v19, v16
	v_cmp_eq_u32_e32 vcc, s13, v19
	s_cbranch_vccnz .LBB0_1177
	s_and_b32 s20, s26, 0xff
	s_cmp_eq_u32 s20, 0
	s_mov_b64 s[20:21], -1
	s_mov_b64 s[24:25], -1
	s_sleep 3
	s_cbranch_scc1 .LBB0_1182
	s_and_b64 vcc, exec, s[24:25]
	s_cbranch_vccz .LBB0_1177

.LBB0_1196:
	s_and_b32 s26, s13, 0xff
	s_mov_b64 s[24:25], -1
	s_cmp_lg_u32 s26, 0
	s_mov_b64 s[28:29], -1
	s_sleep 3
	s_cbranch_scc0 .LBB0_1199
	s_and_b64 vcc, exec, s[28:29]
	s_cbranch_vccz .LBB0_1195

.LBB0_1213:
	s_and_b32 s26, s13, 0xff
	s_cmp_lg_u32 s26, 0
	s_mov_b64 s[28:29], -1
	s_sleep 3
	s_cbranch_scc0 .LBB0_1216
	s_mov_b64 s[30:31], -1
	s_and_b64 vcc, exec, s[28:29]
	s_cbranch_vccz .LBB0_1212

.LBB0_1239:
	global_load_dword v16, v17, s[40:41] offset:1024 sc1
	s_waitcnt lgkmcnt(0)
	global_load_dword v1, v17, s[40:41] offset:1280 sc1
	global_load_dword v2, v17, s[40:41] offset:1536 sc1
	global_load_dword v3, v17, s[40:41] offset:1792 sc1
	global_load_dword v4, v17, s[40:41] offset:2048 sc1
	global_load_dword v5, v17, s[40:41] offset:2304 sc1
	global_load_dword v6, v17, s[40:41] offset:2560 sc1
	global_load_dword v7, v17, s[40:41] offset:2816 sc1
	global_load_dword v8, v17, s[40:41] offset:3072 sc1
	global_load_dword v9, v17, s[40:41] offset:3328 sc1
	global_load_dword v10, v17, s[40:41] offset:3584 sc1
	global_load_dword v11, v17, s[40:41] offset:3840 sc1
	global_load_dword v12, v17, s[8:9] sc1
	global_load_dword v13, v17, s[10:11] sc1
	global_load_dword v14, v17, s[16:17] sc1
	global_load_dword v15, v17, s[18:19] sc1
	s_mov_b64 s[20:21], -1
	s_mov_b64 s[22:23], -1
	s_waitcnt vmcnt(14)
	v_add_u32_e32 v18, v1, v16
	s_waitcnt vmcnt(13)
	v_add_u32_e32 v18, v18, v2
	s_waitcnt vmcnt(12)
	v_add_u32_e32 v18, v18, v3
	s_waitcnt vmcnt(11)
	v_add_u32_e32 v18, v18, v4
	s_waitcnt vmcnt(10)
	v_add_u32_e32 v18, v18, v5
	s_waitcnt vmcnt(9)
	v_add_u32_e32 v18, v18, v6
	s_waitcnt vmcnt(8)
	v_add_u32_e32 v18, v18, v7
	s_waitcnt vmcnt(7)
	v_add_u32_e32 v18, v18, v8
	s_waitcnt vmcnt(6)
	v_add_u32_e32 v18, v18, v9
	s_waitcnt vmcnt(5)
	v_add_u32_e32 v18, v18, v10
	s_waitcnt vmcnt(4)
	v_add_u32_e32 v18, v18, v11
	s_waitcnt vmcnt(3)
	v_add_u32_e32 v18, v18, v12
	s_waitcnt vmcnt(2)
	v_add_u32_e32 v18, v18, v13
	s_waitcnt vmcnt(1)
	v_add_u32_e32 v18, v18, v14
	s_waitcnt vmcnt(0)
	v_add_u32_e32 v18, v18, v15
	v_cmp_eq_u32_e32 vcc, s13, v18
	s_cbranch_vccnz .LBB0_1238
	s_and_b32 s20, s26, 0xff
	s_cmp_eq_u32 s20, 0
	s_mov_b64 s[20:21], -1
	s_mov_b64 s[24:25], -1
	s_sleep 3
	s_cbranch_scc1 .LBB0_1243
	s_and_b64 vcc, exec, s[24:25]
	s_cbranch_vccz .LBB0_1238

.LBB0_1274:
	s_and_b32 s28, s13, 0xff
	s_cmp_lg_u32 s28, 0
	s_mov_b64 s[30:31], -1
	s_sleep 3
	s_cbranch_scc0 .LBB0_1277
	s_mov_b64 s[36:37], -1
	s_and_b64 vcc, exec, s[30:31]
	s_cbranch_vccz .LBB0_1273

.LBB0_1399:
	global_load_dword v16, v17, s[40:41] offset:1024 sc1
	s_waitcnt lgkmcnt(0)
	global_load_dword v1, v17, s[40:41] offset:1280 sc1
	global_load_dword v2, v17, s[40:41] offset:1536 sc1
	global_load_dword v3, v17, s[40:41] offset:1792 sc1
	global_load_dword v4, v17, s[40:41] offset:2048 sc1
	global_load_dword v5, v17, s[40:41] offset:2304 sc1
	global_load_dword v6, v17, s[40:41] offset:2560 sc1
	global_load_dword v7, v17, s[40:41] offset:2816 sc1
	global_load_dword v8, v17, s[40:41] offset:3072 sc1
	global_load_dword v9, v17, s[40:41] offset:3328 sc1
	global_load_dword v10, v17, s[40:41] offset:3584 sc1
	global_load_dword v11, v17, s[40:41] offset:3840 sc1
	global_load_dword v12, v17, s[2:3] sc1
	global_load_dword v13, v17, s[4:5] sc1
	global_load_dword v14, v17, s[6:7] sc1
	global_load_dword v15, v17, s[8:9] sc1
	s_mov_b64 s[10:11], -1
	s_mov_b64 s[12:13], -1
	s_waitcnt vmcnt(14)
	v_add_u32_e32 v18, v1, v16
	s_waitcnt vmcnt(13)
	v_add_u32_e32 v18, v18, v2
	s_waitcnt vmcnt(12)
	v_add_u32_e32 v18, v18, v3
	s_waitcnt vmcnt(11)
	v_add_u32_e32 v18, v18, v4
	s_waitcnt vmcnt(10)
	v_add_u32_e32 v18, v18, v5
	s_waitcnt vmcnt(9)
	v_add_u32_e32 v18, v18, v6
	s_waitcnt vmcnt(8)
	v_add_u32_e32 v18, v18, v7
	s_waitcnt vmcnt(7)
	v_add_u32_e32 v18, v18, v8
	s_waitcnt vmcnt(6)
	v_add_u32_e32 v18, v18, v9
	s_waitcnt vmcnt(5)
	v_add_u32_e32 v18, v18, v10
	s_waitcnt vmcnt(4)
	v_add_u32_e32 v18, v18, v11
	s_waitcnt vmcnt(3)
	v_add_u32_e32 v18, v18, v12
	s_waitcnt vmcnt(2)
	v_add_u32_e32 v18, v18, v13
	s_waitcnt vmcnt(1)
	v_add_u32_e32 v18, v18, v14
	s_waitcnt vmcnt(0)
	v_add_u32_e32 v18, v18, v15
	v_cmp_eq_u32_e32 vcc, s16, v18
	s_cbranch_vccnz .LBB0_1398
	s_and_b32 s10, s17, 0xff
	s_cmp_eq_u32 s10, 0
	s_mov_b64 s[10:11], -1
	s_mov_b64 s[14:15], -1
	s_sleep 3
	s_cbranch_scc1 .LBB0_1403
	s_and_b64 vcc, exec, s[14:15]
	s_cbranch_vccz .LBB0_1398

.LBB0_1417:
	s_and_b32 s16, s20, 0xff
	s_mov_b64 s[14:15], -1
	s_cmp_lg_u32 s16, 0
	s_mov_b64 s[18:19], -1
	s_sleep 3
	s_cbranch_scc0 .LBB0_1420
	s_and_b64 vcc, exec, s[18:19]
	s_cbranch_vccz .LBB0_1416

.LBB0_1434:
	s_and_b32 s16, s22, 0xff
	s_cmp_lg_u32 s16, 0
	s_mov_b64 s[18:19], -1
	s_sleep 3
	s_cbranch_scc0 .LBB0_1437
	s_mov_b64 s[20:21], -1
	s_and_b64 vcc, exec, s[18:19]
	s_cbranch_vccz .LBB0_1433

.LBB0_1457:
	s_sleep 3
	global_load_dword v2, v0, s[2:3] offset:32 sc1
	s_waitcnt vmcnt(0)
	v_and_b32_e32 v2, 0xffff0000, v2
	v_cmp_ne_u32_e32 vcc, v2, v1
	s_or_b64 s[4:5], vcc, s[4:5]
	s_andn2_b64 exec, exec, s[4:5]
	s_cbranch_execnz .LBB0_1457
